# prologue: W_in_even transpose tiles issue their 8 row loads together (were one load per full wait)
# baseline (speedup 1.0000x reference)
; DI int opaque_tid() { int t = threadIdx.x; asm volatile("" : "+v"(t)); return t; }
; __host__ __device__ __forceinline__ int phys_col(int n) { return (n & ~255) + 128 * ((n >> 5) & 1) + 32 * ((n >> 6) & 3) + (n & 31); }
; DI void transpose_tile(const float* W, int K, int N, bf16* WT, int mapmode, int tile, float* scr, const float* kgain = nullptr) {
;   const int tid = opaque_tid();
;   const int ntn = (N + 63) >> 6, kt = tile / ntn, nt = tile % ntn, k0 = kt * 64, n0 = nt * 64;
; #pragma unroll
;   for (int i = 0; i < 8; ++i) {
;     const int kk = (tid >> 6) + 8 * i, nn = tid & 63, n = n0 + nn;
;     scr[kk * 65 + nn] = (n < N) ? W[(size_t)(k0 + kk) * N + n] * (kgain ? kgain[k0 + kk] : 1.f) : 0.f;
;   }
;   __syncthreads();
;   {
;     const int nn = tid >> 3, kc = tid & 7, n = n0 + nn;
;     if (n < N) {
;       const int dst = mapmode == 1 ? phys_col(map_even(n)) : (mapmode == 2 ? phys_col(n) : n);
.LBB0_67:
	s_andn2_b64 vcc, exec, s[4:5]
	s_cbranch_vccnz .LBB0_11
	s_mul_hi_i32 s4, s48, 0x2aaaaaab
	s_lshr_b32 s5, s4, 31
	s_ashr_i32 s4, s4, 3
	v_mov_b32_e32 v20, v182
	s_add_i32 s5, s4, s5
	s_mul_i32 s28, s5, 0xc00
	v_and_b32_e32 v25, 63, v20
	v_subrev_u32_e32 v22, s28, v25
	v_add_u32_e32 v22, s33, v22
	v_ashrrev_i32_e32 v23, 31, v22
	s_lshl_b32 s4, s5, 6
	v_ashrrev_i32_e32 v24, 6, v20
	v_cmp_gt_i32_e32 vcc, s44, v22
	v_lshl_add_u64 v[22:23], v[22:23], 2, s[6:7]
	v_mov_b32_e32 v240, 0
	v_mov_b32_e32 v241, 0
	v_mov_b32_e32 v242, 0
	v_mov_b32_e32 v243, 0
	v_mov_b32_e32 v244, 0
	v_mov_b32_e32 v245, 0
	v_mov_b32_e32 v246, 0
	v_mov_b32_e32 v247, 0
	s_and_saveexec_b64 s[30:31], vcc
	s_cbranch_execz .Lt0_noload
	v_add_u32_e32 v27, s4, v24
	v_mad_i64_i32 v[28:29], s[34:35], v27, s45, v[22:23]
	global_load_dword v240, v[28:29], off
	v_add3_u32 v27, v24, s4, 8
	v_mad_i64_i32 v[28:29], s[34:35], v27, s45, v[22:23]
	global_load_dword v241, v[28:29], off
	v_add3_u32 v27, v24, s4, 16
	v_mad_i64_i32 v[28:29], s[34:35], v27, s45, v[22:23]
	global_load_dword v242, v[28:29], off
	v_add3_u32 v27, v24, s4, 24
	v_mad_i64_i32 v[28:29], s[34:35], v27, s45, v[22:23]
	global_load_dword v243, v[28:29], off
	v_add3_u32 v27, v24, s4, 32
	v_mad_i64_i32 v[28:29], s[34:35], v27, s45, v[22:23]
	global_load_dword v244, v[28:29], off
	v_add3_u32 v27, v24, s4, 40
	v_mad_i64_i32 v[28:29], s[34:35], v27, s45, v[22:23]
	global_load_dword v245, v[28:29], off
	v_add3_u32 v27, v24, s4, 48
	v_mad_i64_i32 v[28:29], s[34:35], v27, s45, v[22:23]
	global_load_dword v246, v[28:29], off
	v_add3_u32 v27, v24, s4, 56
	v_mad_i64_i32 v[28:29], s[34:35], v27, s45, v[22:23]
	global_load_dword v247, v[28:29], off
.Lt0_noload:
	s_or_b64 exec, exec, s[30:31]
	v_lshl_add_u32 v25, v25, 2, 0
	v_mul_lo_u32 v28, v24, s41
	v_add_u32_e32 v25, v25, v28
	v_ashrrev_i32_e32 v22, 3, v20
	v_subrev_u32_e32 v23, s28, v22
	v_add_u32_e32 v24, s33, v23
	v_cmp_gt_i32_e32 vcc, s44, v24
	s_waitcnt vmcnt(7)
	ds_write_b32 v25, v240
	s_waitcnt vmcnt(6)
	ds_write_b32 v25, v241 offset:2080
	s_waitcnt vmcnt(5)
	ds_write_b32 v25, v242 offset:4160
	s_waitcnt vmcnt(4)
	ds_write_b32 v25, v243 offset:6240
	s_waitcnt vmcnt(3)
	ds_write_b32 v25, v244 offset:8320
	s_waitcnt vmcnt(2)
	ds_write_b32 v25, v245 offset:10400
	s_waitcnt vmcnt(1)
	ds_write_b32 v25, v246 offset:12480
	s_waitcnt vmcnt(0)
	ds_write_b32 v25, v247 offset:14560
	s_waitcnt lgkmcnt(0)
	s_barrier
	s_and_saveexec_b64 s[30:31], vcc
	s_cbranch_execz .LBB0_10
	s_mul_i32 s5, s5, 48
	s_sub_i32 s5, s48, s5
	v_lshl_add_u32 v23, s5, 6, v22
	v_cmp_lt_i32_e32 vcc, s46, v24
	s_and_saveexec_b64 s[34:35], vcc
	s_cbranch_execz .LBB0_9
	v_cmp_lt_u32_e32 vcc, s47, v24
	s_and_saveexec_b64 s[36:37], vcc
	s_xor_b64 s[36:37], exec, s[36:37]
	v_add_u32_e32 v23, -8, v24
	s_andn2_saveexec_b64 s[36:37], s[36:37]
	s_cbranch_execz .LBB0_8
	v_add_u32_e32 v23, 0x700, v23
	s_branch .LBB0_8

; __device__ __forceinline__ unsigned xb_add(unsigned* p, unsigned v) { return __hip_atomic_fetch_add(p, v, __ATOMIC_RELAXED, __HIP_MEMORY_SCOPE_AGENT); }
; __device__ __forceinline__ void xcd_barrier(const XcdBarrier& b) {
;     ...
;             __builtin_amdgcn_fence(__ATOMIC_ACQUIRE, "agent");
;             xb_add(&bar[XB_XGEN(b.x)], 1u);
;             asm volatile("s_waitcnt vmcnt(0)" ::: "memory");
.LBB0_2573:
	s_or_b64 exec, exec, s[6:7]
	s_mov_b64 s[6:7], exec
	v_mbcnt_lo_u32_b32 v0, s6, 0
	v_mbcnt_hi_u32_b32 v0, s7, v0
	v_cmp_eq_u32_e32 vcc, 0, v0
	s_waitcnt vmcnt(0)
	buffer_inv sc1
	s_and_saveexec_b64 s[8:9], vcc
	s_cbranch_execz .LBB0_2575
	s_bcnt1_i32_b64 s6, s[6:7]
	v_mov_b32_e32 v0, 0x2000
	v_mov_b32_e32 v1, s6
	global_atomic_add v0, v1, s[2:3] offset:1024
	s_nop 0
	s_nop 0
	s_nop 0
	s_nop 0
	s_nop 0
	s_nop 0
	s_nop 0
	s_nop 0
	s_nop 0
	s_nop 0
	s_nop 0
	s_nop 0
	s_nop 0
	s_nop 0
	s_nop 0
	s_nop 0
	s_nop 0
	s_nop 0
	s_nop 0
	s_nop 0
	s_nop 0
	s_nop 0
	s_nop 0
	s_nop 0
	s_nop 0
	s_nop 0
	s_nop 0
	s_nop 0
	s_nop 0
	s_nop 0
	s_nop 0
	s_nop 0
	s_nop 0
	s_nop 0
	s_nop 0
	s_nop 0
	s_nop 0
	s_nop 0
	s_nop 0
	s_nop 0
.LBB0_2575:
	s_or_b64 exec, exec, s[8:9]
	s_waitcnt vmcnt(0)
